# EpiRes epilogue rescheduled so no dependent packed-f32 ops are adjacent (squares interleaved with bf16 converts); otherwise as v10
# speedup vs baseline: 1.0026x; 1.0026x over previous
.Lepi_p4_nobar:
	s_waitcnt vmcnt(15)
	v_lshlrev_b32_e32 v244, 16, v156
	v_and_b32_e32 v245, 0xffff0000, v156
	v_lshlrev_b32_e32 v246, 16, v157
	v_and_b32_e32 v247, 0xffff0000, v157
	v_lshlrev_b32_e32 v250, 16, v158
	v_and_b32_e32 v251, 0xffff0000, v158
	v_lshlrev_b32_e32 v252, 16, v159
	v_and_b32_e32 v253, 0xffff0000, v159
	v_pk_add_f32 v[124:125], v[124:125], v[244:245]
	v_pk_add_f32 v[126:127], v[126:127], v[246:247]
	v_pk_add_f32 v[120:121], v[120:121], v[250:251]
	v_pk_add_f32 v[122:123], v[122:123], v[252:253]
	v_pk_mul_f32 v[254:255], v[124:125], v[124:125]
	v_cvt_pk_bf16_f32 v124, v124, v125
	v_pk_fma_f32 v[254:255], v[126:127], v[126:127], v[254:255]
	v_cvt_pk_bf16_f32 v125, v126, v127
	v_pk_fma_f32 v[254:255], v[120:121], v[120:121], v[254:255]
	v_cvt_pk_bf16_f32 v126, v120, v121
	v_pk_fma_f32 v[254:255], v[122:123], v[122:123], v[254:255]
	v_cvt_pk_bf16_f32 v127, v122, v123
	global_store_dwordx4 v228, v[124:127], s[20:21]
	s_waitcnt vmcnt(15)
	v_lshlrev_b32_e32 v244, 16, v160
	v_and_b32_e32 v245, 0xffff0000, v160
	v_lshlrev_b32_e32 v246, 16, v161
	v_and_b32_e32 v247, 0xffff0000, v161
	v_lshlrev_b32_e32 v250, 16, v162
	v_and_b32_e32 v251, 0xffff0000, v162
	v_lshlrev_b32_e32 v252, 16, v163
	v_and_b32_e32 v253, 0xffff0000, v163
	v_pk_add_f32 v[116:117], v[116:117], v[244:245]
	v_pk_add_f32 v[118:119], v[118:119], v[246:247]
	v_pk_add_f32 v[112:113], v[112:113], v[250:251]
	v_pk_add_f32 v[114:115], v[114:115], v[252:253]
	v_pk_fma_f32 v[254:255], v[116:117], v[116:117], v[254:255]
	v_cvt_pk_bf16_f32 v116, v116, v117
	v_pk_fma_f32 v[254:255], v[118:119], v[118:119], v[254:255]
	v_cvt_pk_bf16_f32 v117, v118, v119
	v_pk_fma_f32 v[254:255], v[112:113], v[112:113], v[254:255]
	v_cvt_pk_bf16_f32 v118, v112, v113
	v_pk_fma_f32 v[254:255], v[114:115], v[114:115], v[254:255]
	v_cvt_pk_bf16_f32 v119, v114, v115
	global_store_dwordx4 v228, v[116:119], s[20:21] offset:256
	v_add_f32_e32 v112, v254, v255
	s_waitcnt vmcnt(15)
	v_lshlrev_b32_e32 v244, 16, v164
	v_and_b32_e32 v245, 0xffff0000, v164
	v_lshlrev_b32_e32 v246, 16, v165
	v_and_b32_e32 v247, 0xffff0000, v165
	v_lshlrev_b32_e32 v250, 16, v166
	v_and_b32_e32 v251, 0xffff0000, v166
	v_lshlrev_b32_e32 v252, 16, v167
	v_and_b32_e32 v253, 0xffff0000, v167
	v_pk_add_f32 v[108:109], v[108:109], v[244:245]
	v_pk_add_f32 v[110:111], v[110:111], v[246:247]
	v_pk_add_f32 v[104:105], v[104:105], v[250:251]
	v_pk_add_f32 v[106:107], v[106:107], v[252:253]
	v_pk_mul_f32 v[254:255], v[108:109], v[108:109]
	v_cvt_pk_bf16_f32 v108, v108, v109
	v_pk_fma_f32 v[254:255], v[110:111], v[110:111], v[254:255]
	v_cvt_pk_bf16_f32 v109, v110, v111
	v_pk_fma_f32 v[254:255], v[104:105], v[104:105], v[254:255]
	v_cvt_pk_bf16_f32 v110, v104, v105
	v_pk_fma_f32 v[254:255], v[106:107], v[106:107], v[254:255]
	v_cvt_pk_bf16_f32 v111, v106, v107
	global_store_dwordx4 v229, v[108:111], s[20:21]
	s_waitcnt vmcnt(15)
	v_lshlrev_b32_e32 v244, 16, v168
	v_and_b32_e32 v245, 0xffff0000, v168
	v_lshlrev_b32_e32 v246, 16, v169
	v_and_b32_e32 v247, 0xffff0000, v169
	v_lshlrev_b32_e32 v250, 16, v170
	v_and_b32_e32 v251, 0xffff0000, v170
	v_lshlrev_b32_e32 v252, 16, v171
	v_and_b32_e32 v253, 0xffff0000, v171
	v_pk_add_f32 v[100:101], v[100:101], v[244:245]
	v_pk_add_f32 v[102:103], v[102:103], v[246:247]
	v_pk_add_f32 v[96:97], v[96:97], v[250:251]
	v_pk_add_f32 v[98:99], v[98:99], v[252:253]
	v_pk_fma_f32 v[254:255], v[100:101], v[100:101], v[254:255]
	v_cvt_pk_bf16_f32 v100, v100, v101
	v_pk_fma_f32 v[254:255], v[102:103], v[102:103], v[254:255]
	v_cvt_pk_bf16_f32 v101, v102, v103
	v_pk_fma_f32 v[254:255], v[96:97], v[96:97], v[254:255]
	v_cvt_pk_bf16_f32 v102, v96, v97
	v_pk_fma_f32 v[254:255], v[98:99], v[98:99], v[254:255]
	v_cvt_pk_bf16_f32 v103, v98, v99
	global_store_dwordx4 v229, v[100:103], s[20:21] offset:256
	v_add_f32_e32 v96, v254, v255
	s_waitcnt vmcnt(15)
	v_lshlrev_b32_e32 v244, 16, v172
	v_and_b32_e32 v245, 0xffff0000, v172
	v_lshlrev_b32_e32 v246, 16, v173
	v_and_b32_e32 v247, 0xffff0000, v173
	v_lshlrev_b32_e32 v250, 16, v174
	v_and_b32_e32 v251, 0xffff0000, v174
	v_lshlrev_b32_e32 v252, 16, v175
	v_and_b32_e32 v253, 0xffff0000, v175
	v_pk_add_f32 v[92:93], v[92:93], v[244:245]
	v_pk_add_f32 v[94:95], v[94:95], v[246:247]
	v_pk_add_f32 v[88:89], v[88:89], v[250:251]
	v_pk_add_f32 v[90:91], v[90:91], v[252:253]
	v_pk_mul_f32 v[254:255], v[92:93], v[92:93]
	v_cvt_pk_bf16_f32 v92, v92, v93
	v_pk_fma_f32 v[254:255], v[94:95], v[94:95], v[254:255]
	v_cvt_pk_bf16_f32 v93, v94, v95
	v_pk_fma_f32 v[254:255], v[88:89], v[88:89], v[254:255]
	v_cvt_pk_bf16_f32 v94, v88, v89
	v_pk_fma_f32 v[254:255], v[90:91], v[90:91], v[254:255]
	v_cvt_pk_bf16_f32 v95, v90, v91
	global_store_dwordx4 v230, v[92:95], s[20:21]
	s_waitcnt vmcnt(15)
	v_lshlrev_b32_e32 v244, 16, v176
	v_and_b32_e32 v245, 0xffff0000, v176
	v_lshlrev_b32_e32 v246, 16, v177
	v_and_b32_e32 v247, 0xffff0000, v177
	v_lshlrev_b32_e32 v250, 16, v178
	v_and_b32_e32 v251, 0xffff0000, v178
	v_lshlrev_b32_e32 v252, 16, v179
	v_and_b32_e32 v253, 0xffff0000, v179
	v_pk_add_f32 v[84:85], v[84:85], v[244:245]
	v_pk_add_f32 v[86:87], v[86:87], v[246:247]
	v_pk_add_f32 v[80:81], v[80:81], v[250:251]
	v_pk_add_f32 v[82:83], v[82:83], v[252:253]
	v_pk_fma_f32 v[254:255], v[84:85], v[84:85], v[254:255]
	v_cvt_pk_bf16_f32 v84, v84, v85
	v_pk_fma_f32 v[254:255], v[86:87], v[86:87], v[254:255]
	v_cvt_pk_bf16_f32 v85, v86, v87
	v_pk_fma_f32 v[254:255], v[80:81], v[80:81], v[254:255]
	v_cvt_pk_bf16_f32 v86, v80, v81
	v_pk_fma_f32 v[254:255], v[82:83], v[82:83], v[254:255]
	v_cvt_pk_bf16_f32 v87, v82, v83
	global_store_dwordx4 v230, v[84:87], s[20:21] offset:256
	v_add_f32_e32 v80, v254, v255
	s_waitcnt vmcnt(15)
	v_lshlrev_b32_e32 v244, 16, v180
	v_and_b32_e32 v245, 0xffff0000, v180
	v_lshlrev_b32_e32 v246, 16, v181
	v_and_b32_e32 v247, 0xffff0000, v181
	v_lshlrev_b32_e32 v250, 16, v182
	v_and_b32_e32 v251, 0xffff0000, v182
	v_lshlrev_b32_e32 v252, 16, v183
	v_and_b32_e32 v253, 0xffff0000, v183
	v_pk_add_f32 v[76:77], v[76:77], v[244:245]
	v_pk_add_f32 v[78:79], v[78:79], v[246:247]
	v_pk_add_f32 v[72:73], v[72:73], v[250:251]
	v_pk_add_f32 v[74:75], v[74:75], v[252:253]
	v_pk_mul_f32 v[254:255], v[76:77], v[76:77]
	v_cvt_pk_bf16_f32 v76, v76, v77
	v_pk_fma_f32 v[254:255], v[78:79], v[78:79], v[254:255]
	v_cvt_pk_bf16_f32 v77, v78, v79
	v_pk_fma_f32 v[254:255], v[72:73], v[72:73], v[254:255]
	v_cvt_pk_bf16_f32 v78, v72, v73
	v_pk_fma_f32 v[254:255], v[74:75], v[74:75], v[254:255]
	v_cvt_pk_bf16_f32 v79, v74, v75
	global_store_dwordx4 v231, v[76:79], s[20:21]
	s_waitcnt vmcnt(15)
	v_lshlrev_b32_e32 v244, 16, v184
	v_and_b32_e32 v245, 0xffff0000, v184
	v_lshlrev_b32_e32 v246, 16, v185
	v_and_b32_e32 v247, 0xffff0000, v185
	v_lshlrev_b32_e32 v250, 16, v186
	v_and_b32_e32 v251, 0xffff0000, v186
	v_lshlrev_b32_e32 v252, 16, v187
	v_and_b32_e32 v253, 0xffff0000, v187
	v_pk_add_f32 v[68:69], v[68:69], v[244:245]
	v_pk_add_f32 v[70:71], v[70:71], v[246:247]
	v_pk_add_f32 v[64:65], v[64:65], v[250:251]
	v_pk_add_f32 v[66:67], v[66:67], v[252:253]
	v_pk_fma_f32 v[254:255], v[68:69], v[68:69], v[254:255]
	v_cvt_pk_bf16_f32 v68, v68, v69
	v_pk_fma_f32 v[254:255], v[70:71], v[70:71], v[254:255]
	v_cvt_pk_bf16_f32 v69, v70, v71
	v_pk_fma_f32 v[254:255], v[64:65], v[64:65], v[254:255]
	v_cvt_pk_bf16_f32 v70, v64, v65
	v_pk_fma_f32 v[254:255], v[66:67], v[66:67], v[254:255]
	v_cvt_pk_bf16_f32 v71, v66, v67
	global_store_dwordx4 v231, v[68:71], s[20:21] offset:256
	v_add_f32_e32 v64, v254, v255
	s_waitcnt vmcnt(15)
	v_lshlrev_b32_e32 v244, 16, v188
	v_and_b32_e32 v245, 0xffff0000, v188
	v_lshlrev_b32_e32 v246, 16, v189
	v_and_b32_e32 v247, 0xffff0000, v189
	v_lshlrev_b32_e32 v250, 16, v190
	v_and_b32_e32 v251, 0xffff0000, v190
	v_lshlrev_b32_e32 v252, 16, v191
	v_and_b32_e32 v253, 0xffff0000, v191
	v_pk_add_f32 v[60:61], v[60:61], v[244:245]
	v_pk_add_f32 v[62:63], v[62:63], v[246:247]
	v_pk_add_f32 v[56:57], v[56:57], v[250:251]
	v_pk_add_f32 v[58:59], v[58:59], v[252:253]
	v_pk_mul_f32 v[254:255], v[60:61], v[60:61]
	v_cvt_pk_bf16_f32 v60, v60, v61
	v_pk_fma_f32 v[254:255], v[62:63], v[62:63], v[254:255]
	v_cvt_pk_bf16_f32 v61, v62, v63
	v_pk_fma_f32 v[254:255], v[56:57], v[56:57], v[254:255]
	v_cvt_pk_bf16_f32 v62, v56, v57
	v_pk_fma_f32 v[254:255], v[58:59], v[58:59], v[254:255]
	v_cvt_pk_bf16_f32 v63, v58, v59
	global_store_dwordx4 v232, v[60:63], s[20:21]
	s_waitcnt vmcnt(15)
	v_lshlrev_b32_e32 v244, 16, v192
	v_and_b32_e32 v245, 0xffff0000, v192
	v_lshlrev_b32_e32 v246, 16, v193
	v_and_b32_e32 v247, 0xffff0000, v193
	v_lshlrev_b32_e32 v250, 16, v194
	v_and_b32_e32 v251, 0xffff0000, v194
	v_lshlrev_b32_e32 v252, 16, v195
	v_and_b32_e32 v253, 0xffff0000, v195
	v_pk_add_f32 v[52:53], v[52:53], v[244:245]
	v_pk_add_f32 v[54:55], v[54:55], v[246:247]
	v_pk_add_f32 v[48:49], v[48:49], v[250:251]
	v_pk_add_f32 v[50:51], v[50:51], v[252:253]
	v_pk_fma_f32 v[254:255], v[52:53], v[52:53], v[254:255]
	v_cvt_pk_bf16_f32 v52, v52, v53
	v_pk_fma_f32 v[254:255], v[54:55], v[54:55], v[254:255]
	v_cvt_pk_bf16_f32 v53, v54, v55
	v_pk_fma_f32 v[254:255], v[48:49], v[48:49], v[254:255]
	v_cvt_pk_bf16_f32 v54, v48, v49
	v_pk_fma_f32 v[254:255], v[50:51], v[50:51], v[254:255]
	v_cvt_pk_bf16_f32 v55, v50, v51
	global_store_dwordx4 v232, v[52:55], s[20:21] offset:256
	v_add_f32_e32 v48, v254, v255
	s_waitcnt vmcnt(15)
	v_lshlrev_b32_e32 v244, 16, v196
	v_and_b32_e32 v245, 0xffff0000, v196
	v_lshlrev_b32_e32 v246, 16, v197
	v_and_b32_e32 v247, 0xffff0000, v197
	v_lshlrev_b32_e32 v250, 16, v198
	v_and_b32_e32 v251, 0xffff0000, v198
	v_lshlrev_b32_e32 v252, 16, v199
	v_and_b32_e32 v253, 0xffff0000, v199
	v_pk_add_f32 v[44:45], v[44:45], v[244:245]
	v_pk_add_f32 v[46:47], v[46:47], v[246:247]
	v_pk_add_f32 v[40:41], v[40:41], v[250:251]
	v_pk_add_f32 v[42:43], v[42:43], v[252:253]
	v_pk_mul_f32 v[254:255], v[44:45], v[44:45]
	v_cvt_pk_bf16_f32 v44, v44, v45
	v_pk_fma_f32 v[254:255], v[46:47], v[46:47], v[254:255]
	v_cvt_pk_bf16_f32 v45, v46, v47
	v_pk_fma_f32 v[254:255], v[40:41], v[40:41], v[254:255]
	v_cvt_pk_bf16_f32 v46, v40, v41
	v_pk_fma_f32 v[254:255], v[42:43], v[42:43], v[254:255]
	v_cvt_pk_bf16_f32 v47, v42, v43
	global_store_dwordx4 v233, v[44:47], s[20:21]
	s_waitcnt vmcnt(15)
	v_lshlrev_b32_e32 v244, 16, v200
	v_and_b32_e32 v245, 0xffff0000, v200
	v_lshlrev_b32_e32 v246, 16, v201
	v_and_b32_e32 v247, 0xffff0000, v201
	v_lshlrev_b32_e32 v250, 16, v202
	v_and_b32_e32 v251, 0xffff0000, v202
	v_lshlrev_b32_e32 v252, 16, v203
	v_and_b32_e32 v253, 0xffff0000, v203
	v_pk_add_f32 v[36:37], v[36:37], v[244:245]
	v_pk_add_f32 v[38:39], v[38:39], v[246:247]
	v_pk_add_f32 v[32:33], v[32:33], v[250:251]
	v_pk_add_f32 v[34:35], v[34:35], v[252:253]
	v_pk_fma_f32 v[254:255], v[36:37], v[36:37], v[254:255]
	v_cvt_pk_bf16_f32 v36, v36, v37
	v_pk_fma_f32 v[254:255], v[38:39], v[38:39], v[254:255]
	v_cvt_pk_bf16_f32 v37, v38, v39
	v_pk_fma_f32 v[254:255], v[32:33], v[32:33], v[254:255]
	v_cvt_pk_bf16_f32 v38, v32, v33
	v_pk_fma_f32 v[254:255], v[34:35], v[34:35], v[254:255]
	v_cvt_pk_bf16_f32 v39, v34, v35
	global_store_dwordx4 v233, v[36:39], s[20:21] offset:256
	v_add_f32_e32 v32, v254, v255
	s_waitcnt vmcnt(15)
	v_lshlrev_b32_e32 v244, 16, v204
	v_and_b32_e32 v245, 0xffff0000, v204
	v_lshlrev_b32_e32 v246, 16, v205
	v_and_b32_e32 v247, 0xffff0000, v205
	v_lshlrev_b32_e32 v250, 16, v206
	v_and_b32_e32 v251, 0xffff0000, v206
	v_lshlrev_b32_e32 v252, 16, v207
	v_and_b32_e32 v253, 0xffff0000, v207
	v_pk_add_f32 v[28:29], v[28:29], v[244:245]
	v_pk_add_f32 v[30:31], v[30:31], v[246:247]
	v_pk_add_f32 v[24:25], v[24:25], v[250:251]
	v_pk_add_f32 v[26:27], v[26:27], v[252:253]
	v_pk_mul_f32 v[254:255], v[28:29], v[28:29]
	v_cvt_pk_bf16_f32 v28, v28, v29
	v_pk_fma_f32 v[254:255], v[30:31], v[30:31], v[254:255]
	v_cvt_pk_bf16_f32 v29, v30, v31
	v_pk_fma_f32 v[254:255], v[24:25], v[24:25], v[254:255]
	v_cvt_pk_bf16_f32 v30, v24, v25
	v_pk_fma_f32 v[254:255], v[26:27], v[26:27], v[254:255]
	v_cvt_pk_bf16_f32 v31, v26, v27
	global_store_dwordx4 v234, v[28:31], s[20:21]
	s_waitcnt vmcnt(15)
	v_lshlrev_b32_e32 v244, 16, v208
	v_and_b32_e32 v245, 0xffff0000, v208
	v_lshlrev_b32_e32 v246, 16, v209
	v_and_b32_e32 v247, 0xffff0000, v209
	v_lshlrev_b32_e32 v250, 16, v210
	v_and_b32_e32 v251, 0xffff0000, v210
	v_lshlrev_b32_e32 v252, 16, v211
	v_and_b32_e32 v253, 0xffff0000, v211
	v_pk_add_f32 v[20:21], v[20:21], v[244:245]
	v_pk_add_f32 v[22:23], v[22:23], v[246:247]
	v_pk_add_f32 v[16:17], v[16:17], v[250:251]
	v_pk_add_f32 v[18:19], v[18:19], v[252:253]
	v_pk_fma_f32 v[254:255], v[20:21], v[20:21], v[254:255]
	v_cvt_pk_bf16_f32 v20, v20, v21
	v_pk_fma_f32 v[254:255], v[22:23], v[22:23], v[254:255]
	v_cvt_pk_bf16_f32 v21, v22, v23
	v_pk_fma_f32 v[254:255], v[16:17], v[16:17], v[254:255]
	v_cvt_pk_bf16_f32 v22, v16, v17
	v_pk_fma_f32 v[254:255], v[18:19], v[18:19], v[254:255]
	v_cvt_pk_bf16_f32 v23, v18, v19
	global_store_dwordx4 v234, v[20:23], s[20:21] offset:256
	v_add_f32_e32 v16, v254, v255
	s_waitcnt vmcnt(15)
	v_lshlrev_b32_e32 v244, 16, v212
	v_and_b32_e32 v245, 0xffff0000, v212
	v_lshlrev_b32_e32 v246, 16, v213
	v_and_b32_e32 v247, 0xffff0000, v213
	v_lshlrev_b32_e32 v250, 16, v214
	v_and_b32_e32 v251, 0xffff0000, v214
	v_lshlrev_b32_e32 v252, 16, v215
	v_and_b32_e32 v253, 0xffff0000, v215
	v_pk_add_f32 v[12:13], v[12:13], v[244:245]
	v_pk_add_f32 v[14:15], v[14:15], v[246:247]
	v_pk_add_f32 v[8:9], v[8:9], v[250:251]
	v_pk_add_f32 v[10:11], v[10:11], v[252:253]
	v_pk_mul_f32 v[254:255], v[12:13], v[12:13]
	v_cvt_pk_bf16_f32 v12, v12, v13
	v_pk_fma_f32 v[254:255], v[14:15], v[14:15], v[254:255]
	v_cvt_pk_bf16_f32 v13, v14, v15
	v_pk_fma_f32 v[254:255], v[8:9], v[8:9], v[254:255]
	v_cvt_pk_bf16_f32 v14, v8, v9
	v_pk_fma_f32 v[254:255], v[10:11], v[10:11], v[254:255]
	v_cvt_pk_bf16_f32 v15, v10, v11
	global_store_dwordx4 v235, v[12:15], s[20:21]
	s_waitcnt vmcnt(15)
	v_lshlrev_b32_e32 v244, 16, v224
	v_and_b32_e32 v245, 0xffff0000, v224
	v_lshlrev_b32_e32 v246, 16, v225
	v_and_b32_e32 v247, 0xffff0000, v225
	v_lshlrev_b32_e32 v250, 16, v226
	v_and_b32_e32 v251, 0xffff0000, v226
	v_lshlrev_b32_e32 v252, 16, v227
	v_and_b32_e32 v253, 0xffff0000, v227
	v_pk_add_f32 v[4:5], v[4:5], v[244:245]
	v_pk_add_f32 v[6:7], v[6:7], v[246:247]
	v_pk_add_f32 v[0:1], v[0:1], v[250:251]
	v_pk_add_f32 v[2:3], v[2:3], v[252:253]
	v_pk_fma_f32 v[254:255], v[4:5], v[4:5], v[254:255]
	v_cvt_pk_bf16_f32 v4, v4, v5
	v_pk_fma_f32 v[254:255], v[6:7], v[6:7], v[254:255]
	v_cvt_pk_bf16_f32 v5, v6, v7
	v_pk_fma_f32 v[254:255], v[0:1], v[0:1], v[254:255]
	v_cvt_pk_bf16_f32 v6, v0, v1
	v_pk_fma_f32 v[254:255], v[2:3], v[2:3], v[254:255]
	v_cvt_pk_bf16_f32 v7, v2, v3
	global_store_dwordx4 v235, v[4:7], s[20:21] offset:256
	v_add_f32_e32 v0, v254, v255
	v_xor_b32_e32 v244, 16, v154
	v_xor_b32_e32 v245, 32, v154
	v_lshlrev_b32_e32 v244, 2, v244
	v_lshlrev_b32_e32 v245, 2, v245
	ds_bpermute_b32 v156, v244, v112
	ds_bpermute_b32 v157, v244, v96
	ds_bpermute_b32 v158, v244, v80
	ds_bpermute_b32 v159, v244, v64
	ds_bpermute_b32 v160, v244, v48
	ds_bpermute_b32 v161, v244, v32
	ds_bpermute_b32 v162, v244, v16
	ds_bpermute_b32 v163, v244, v0
	s_waitcnt lgkmcnt(0)
	v_add_f32_e32 v112, v112, v156
	v_add_f32_e32 v96, v96, v157
	v_add_f32_e32 v80, v80, v158
	v_add_f32_e32 v64, v64, v159
	v_add_f32_e32 v48, v48, v160
	v_add_f32_e32 v32, v32, v161
	v_add_f32_e32 v16, v16, v162
	v_add_f32_e32 v0, v0, v163
	ds_bpermute_b32 v156, v245, v112
	ds_bpermute_b32 v157, v245, v96
	ds_bpermute_b32 v158, v245, v80
	ds_bpermute_b32 v159, v245, v64
	ds_bpermute_b32 v160, v245, v48
	ds_bpermute_b32 v161, v245, v32
	ds_bpermute_b32 v162, v245, v16
	ds_bpermute_b32 v163, v245, v0
	v_lshlrev_b32_e32 v145, 2, v146
	s_waitcnt lgkmcnt(0)
	v_add_f32_e32 v112, v112, v156
	v_add_f32_e32 v96, v96, v157
	v_add_f32_e32 v80, v80, v158
	v_add_f32_e32 v64, v64, v159
	v_add_f32_e32 v48, v48, v160
	v_add_f32_e32 v32, v32, v161
	v_add_f32_e32 v16, v16, v162
	v_add_f32_e32 v0, v0, v163
	s_and_saveexec_b64 s[46:47], s[0:1]
	s_cbranch_execz .Lepi_p4_noatom
	global_atomic_add_f32 v145, v112, s[22:23]
	global_atomic_add_f32 v145, v96, s[22:23] offset:64
	global_atomic_add_f32 v145, v80, s[22:23] offset:128
	global_atomic_add_f32 v145, v64, s[22:23] offset:192
	global_atomic_add_f32 v145, v48, s[22:23] offset:512
	global_atomic_add_f32 v145, v32, s[22:23] offset:576
	global_atomic_add_f32 v145, v16, s[22:23] offset:640
	global_atomic_add_f32 v145, v0, s[22:23] offset:704

.Lepi_p6_nobar:
	s_waitcnt vmcnt(15)
	v_lshlrev_b32_e32 v244, 16, v156
	v_and_b32_e32 v245, 0xffff0000, v156
	v_lshlrev_b32_e32 v246, 16, v157
	v_and_b32_e32 v247, 0xffff0000, v157
	v_lshlrev_b32_e32 v250, 16, v158
	v_and_b32_e32 v251, 0xffff0000, v158
	v_lshlrev_b32_e32 v252, 16, v159
	v_and_b32_e32 v253, 0xffff0000, v159
	v_pk_add_f32 v[124:125], v[124:125], v[244:245]
	v_pk_add_f32 v[126:127], v[126:127], v[246:247]
	v_pk_add_f32 v[120:121], v[120:121], v[250:251]
	v_pk_add_f32 v[122:123], v[122:123], v[252:253]
	v_pk_mul_f32 v[254:255], v[124:125], v[124:125]
	v_cvt_pk_bf16_f32 v124, v124, v125
	v_pk_fma_f32 v[254:255], v[126:127], v[126:127], v[254:255]
	v_cvt_pk_bf16_f32 v125, v126, v127
	v_pk_fma_f32 v[254:255], v[120:121], v[120:121], v[254:255]
	v_cvt_pk_bf16_f32 v126, v120, v121
	v_pk_fma_f32 v[254:255], v[122:123], v[122:123], v[254:255]
	v_cvt_pk_bf16_f32 v127, v122, v123
	global_store_dwordx4 v228, v[124:127], s[20:21]
	s_waitcnt vmcnt(15)
	v_lshlrev_b32_e32 v244, 16, v160
	v_and_b32_e32 v245, 0xffff0000, v160
	v_lshlrev_b32_e32 v246, 16, v161
	v_and_b32_e32 v247, 0xffff0000, v161
	v_lshlrev_b32_e32 v250, 16, v162
	v_and_b32_e32 v251, 0xffff0000, v162
	v_lshlrev_b32_e32 v252, 16, v163
	v_and_b32_e32 v253, 0xffff0000, v163
	v_pk_add_f32 v[116:117], v[116:117], v[244:245]
	v_pk_add_f32 v[118:119], v[118:119], v[246:247]
	v_pk_add_f32 v[112:113], v[112:113], v[250:251]
	v_pk_add_f32 v[114:115], v[114:115], v[252:253]
	v_pk_fma_f32 v[254:255], v[116:117], v[116:117], v[254:255]
	v_cvt_pk_bf16_f32 v116, v116, v117
	v_pk_fma_f32 v[254:255], v[118:119], v[118:119], v[254:255]
	v_cvt_pk_bf16_f32 v117, v118, v119
	v_pk_fma_f32 v[254:255], v[112:113], v[112:113], v[254:255]
	v_cvt_pk_bf16_f32 v118, v112, v113
	v_pk_fma_f32 v[254:255], v[114:115], v[114:115], v[254:255]
	v_cvt_pk_bf16_f32 v119, v114, v115
	global_store_dwordx4 v228, v[116:119], s[20:21] offset:256
	v_add_f32_e32 v112, v254, v255
	s_waitcnt vmcnt(15)
	v_lshlrev_b32_e32 v244, 16, v164
	v_and_b32_e32 v245, 0xffff0000, v164
	v_lshlrev_b32_e32 v246, 16, v165
	v_and_b32_e32 v247, 0xffff0000, v165
	v_lshlrev_b32_e32 v250, 16, v166
	v_and_b32_e32 v251, 0xffff0000, v166
	v_lshlrev_b32_e32 v252, 16, v167
	v_and_b32_e32 v253, 0xffff0000, v167
	v_pk_add_f32 v[108:109], v[108:109], v[244:245]
	v_pk_add_f32 v[110:111], v[110:111], v[246:247]
	v_pk_add_f32 v[104:105], v[104:105], v[250:251]
	v_pk_add_f32 v[106:107], v[106:107], v[252:253]
	v_pk_mul_f32 v[254:255], v[108:109], v[108:109]
	v_cvt_pk_bf16_f32 v108, v108, v109
	v_pk_fma_f32 v[254:255], v[110:111], v[110:111], v[254:255]
	v_cvt_pk_bf16_f32 v109, v110, v111
	v_pk_fma_f32 v[254:255], v[104:105], v[104:105], v[254:255]
	v_cvt_pk_bf16_f32 v110, v104, v105
	v_pk_fma_f32 v[254:255], v[106:107], v[106:107], v[254:255]
	v_cvt_pk_bf16_f32 v111, v106, v107
	global_store_dwordx4 v229, v[108:111], s[20:21]
	s_waitcnt vmcnt(15)
	v_lshlrev_b32_e32 v244, 16, v168
	v_and_b32_e32 v245, 0xffff0000, v168
	v_lshlrev_b32_e32 v246, 16, v169
	v_and_b32_e32 v247, 0xffff0000, v169
	v_lshlrev_b32_e32 v250, 16, v170
	v_and_b32_e32 v251, 0xffff0000, v170
	v_lshlrev_b32_e32 v252, 16, v171
	v_and_b32_e32 v253, 0xffff0000, v171
	v_pk_add_f32 v[100:101], v[100:101], v[244:245]
	v_pk_add_f32 v[102:103], v[102:103], v[246:247]
	v_pk_add_f32 v[96:97], v[96:97], v[250:251]
	v_pk_add_f32 v[98:99], v[98:99], v[252:253]
	v_pk_fma_f32 v[254:255], v[100:101], v[100:101], v[254:255]
	v_cvt_pk_bf16_f32 v100, v100, v101
	v_pk_fma_f32 v[254:255], v[102:103], v[102:103], v[254:255]
	v_cvt_pk_bf16_f32 v101, v102, v103
	v_pk_fma_f32 v[254:255], v[96:97], v[96:97], v[254:255]
	v_cvt_pk_bf16_f32 v102, v96, v97
	v_pk_fma_f32 v[254:255], v[98:99], v[98:99], v[254:255]
	v_cvt_pk_bf16_f32 v103, v98, v99
	global_store_dwordx4 v229, v[100:103], s[20:21] offset:256
	v_add_f32_e32 v96, v254, v255
	s_waitcnt vmcnt(15)
	v_lshlrev_b32_e32 v244, 16, v172
	v_and_b32_e32 v245, 0xffff0000, v172
	v_lshlrev_b32_e32 v246, 16, v173
	v_and_b32_e32 v247, 0xffff0000, v173
	v_lshlrev_b32_e32 v250, 16, v174
	v_and_b32_e32 v251, 0xffff0000, v174
	v_lshlrev_b32_e32 v252, 16, v175
	v_and_b32_e32 v253, 0xffff0000, v175
	v_pk_add_f32 v[92:93], v[92:93], v[244:245]
	v_pk_add_f32 v[94:95], v[94:95], v[246:247]
	v_pk_add_f32 v[88:89], v[88:89], v[250:251]
	v_pk_add_f32 v[90:91], v[90:91], v[252:253]
	v_pk_mul_f32 v[254:255], v[92:93], v[92:93]
	v_cvt_pk_bf16_f32 v92, v92, v93
	v_pk_fma_f32 v[254:255], v[94:95], v[94:95], v[254:255]
	v_cvt_pk_bf16_f32 v93, v94, v95
	v_pk_fma_f32 v[254:255], v[88:89], v[88:89], v[254:255]
	v_cvt_pk_bf16_f32 v94, v88, v89
	v_pk_fma_f32 v[254:255], v[90:91], v[90:91], v[254:255]
	v_cvt_pk_bf16_f32 v95, v90, v91
	global_store_dwordx4 v230, v[92:95], s[20:21]
	s_waitcnt vmcnt(15)
	v_lshlrev_b32_e32 v244, 16, v176
	v_and_b32_e32 v245, 0xffff0000, v176
	v_lshlrev_b32_e32 v246, 16, v177
	v_and_b32_e32 v247, 0xffff0000, v177
	v_lshlrev_b32_e32 v250, 16, v178
	v_and_b32_e32 v251, 0xffff0000, v178
	v_lshlrev_b32_e32 v252, 16, v179
	v_and_b32_e32 v253, 0xffff0000, v179
	v_pk_add_f32 v[84:85], v[84:85], v[244:245]
	v_pk_add_f32 v[86:87], v[86:87], v[246:247]
	v_pk_add_f32 v[80:81], v[80:81], v[250:251]
	v_pk_add_f32 v[82:83], v[82:83], v[252:253]
	v_pk_fma_f32 v[254:255], v[84:85], v[84:85], v[254:255]
	v_cvt_pk_bf16_f32 v84, v84, v85
	v_pk_fma_f32 v[254:255], v[86:87], v[86:87], v[254:255]
	v_cvt_pk_bf16_f32 v85, v86, v87
	v_pk_fma_f32 v[254:255], v[80:81], v[80:81], v[254:255]
	v_cvt_pk_bf16_f32 v86, v80, v81
	v_pk_fma_f32 v[254:255], v[82:83], v[82:83], v[254:255]
	v_cvt_pk_bf16_f32 v87, v82, v83
	global_store_dwordx4 v230, v[84:87], s[20:21] offset:256
	v_add_f32_e32 v80, v254, v255
	s_waitcnt vmcnt(15)
	v_lshlrev_b32_e32 v244, 16, v180
	v_and_b32_e32 v245, 0xffff0000, v180
	v_lshlrev_b32_e32 v246, 16, v181
	v_and_b32_e32 v247, 0xffff0000, v181
	v_lshlrev_b32_e32 v250, 16, v182
	v_and_b32_e32 v251, 0xffff0000, v182
	v_lshlrev_b32_e32 v252, 16, v183
	v_and_b32_e32 v253, 0xffff0000, v183
	v_pk_add_f32 v[76:77], v[76:77], v[244:245]
	v_pk_add_f32 v[78:79], v[78:79], v[246:247]
	v_pk_add_f32 v[72:73], v[72:73], v[250:251]
	v_pk_add_f32 v[74:75], v[74:75], v[252:253]
	v_pk_mul_f32 v[254:255], v[76:77], v[76:77]
	v_cvt_pk_bf16_f32 v76, v76, v77
	v_pk_fma_f32 v[254:255], v[78:79], v[78:79], v[254:255]
	v_cvt_pk_bf16_f32 v77, v78, v79
	v_pk_fma_f32 v[254:255], v[72:73], v[72:73], v[254:255]
	v_cvt_pk_bf16_f32 v78, v72, v73
	v_pk_fma_f32 v[254:255], v[74:75], v[74:75], v[254:255]
	v_cvt_pk_bf16_f32 v79, v74, v75
	global_store_dwordx4 v231, v[76:79], s[20:21]
	s_waitcnt vmcnt(15)
	v_lshlrev_b32_e32 v244, 16, v184
	v_and_b32_e32 v245, 0xffff0000, v184
	v_lshlrev_b32_e32 v246, 16, v185
	v_and_b32_e32 v247, 0xffff0000, v185
	v_lshlrev_b32_e32 v250, 16, v186
	v_and_b32_e32 v251, 0xffff0000, v186
	v_lshlrev_b32_e32 v252, 16, v187
	v_and_b32_e32 v253, 0xffff0000, v187
	v_pk_add_f32 v[68:69], v[68:69], v[244:245]
	v_pk_add_f32 v[70:71], v[70:71], v[246:247]
	v_pk_add_f32 v[64:65], v[64:65], v[250:251]
	v_pk_add_f32 v[66:67], v[66:67], v[252:253]
	v_pk_fma_f32 v[254:255], v[68:69], v[68:69], v[254:255]
	v_cvt_pk_bf16_f32 v68, v68, v69
	v_pk_fma_f32 v[254:255], v[70:71], v[70:71], v[254:255]
	v_cvt_pk_bf16_f32 v69, v70, v71
	v_pk_fma_f32 v[254:255], v[64:65], v[64:65], v[254:255]
	v_cvt_pk_bf16_f32 v70, v64, v65
	v_pk_fma_f32 v[254:255], v[66:67], v[66:67], v[254:255]
	v_cvt_pk_bf16_f32 v71, v66, v67
	global_store_dwordx4 v231, v[68:71], s[20:21] offset:256
	v_add_f32_e32 v64, v254, v255
	s_waitcnt vmcnt(15)
	v_lshlrev_b32_e32 v244, 16, v188
	v_and_b32_e32 v245, 0xffff0000, v188
	v_lshlrev_b32_e32 v246, 16, v189
	v_and_b32_e32 v247, 0xffff0000, v189
	v_lshlrev_b32_e32 v250, 16, v190
	v_and_b32_e32 v251, 0xffff0000, v190
	v_lshlrev_b32_e32 v252, 16, v191
	v_and_b32_e32 v253, 0xffff0000, v191
	v_pk_add_f32 v[60:61], v[60:61], v[244:245]
	v_pk_add_f32 v[62:63], v[62:63], v[246:247]
	v_pk_add_f32 v[56:57], v[56:57], v[250:251]
	v_pk_add_f32 v[58:59], v[58:59], v[252:253]
	v_pk_mul_f32 v[254:255], v[60:61], v[60:61]
	v_cvt_pk_bf16_f32 v60, v60, v61
	v_pk_fma_f32 v[254:255], v[62:63], v[62:63], v[254:255]
	v_cvt_pk_bf16_f32 v61, v62, v63
	v_pk_fma_f32 v[254:255], v[56:57], v[56:57], v[254:255]
	v_cvt_pk_bf16_f32 v62, v56, v57
	v_pk_fma_f32 v[254:255], v[58:59], v[58:59], v[254:255]
	v_cvt_pk_bf16_f32 v63, v58, v59
	global_store_dwordx4 v232, v[60:63], s[20:21]
	s_waitcnt vmcnt(15)
	v_lshlrev_b32_e32 v244, 16, v192
	v_and_b32_e32 v245, 0xffff0000, v192
	v_lshlrev_b32_e32 v246, 16, v193
	v_and_b32_e32 v247, 0xffff0000, v193
	v_lshlrev_b32_e32 v250, 16, v194
	v_and_b32_e32 v251, 0xffff0000, v194
	v_lshlrev_b32_e32 v252, 16, v195
	v_and_b32_e32 v253, 0xffff0000, v195
	v_pk_add_f32 v[52:53], v[52:53], v[244:245]
	v_pk_add_f32 v[54:55], v[54:55], v[246:247]
	v_pk_add_f32 v[48:49], v[48:49], v[250:251]
	v_pk_add_f32 v[50:51], v[50:51], v[252:253]
	v_pk_fma_f32 v[254:255], v[52:53], v[52:53], v[254:255]
	v_cvt_pk_bf16_f32 v52, v52, v53
	v_pk_fma_f32 v[254:255], v[54:55], v[54:55], v[254:255]
	v_cvt_pk_bf16_f32 v53, v54, v55
	v_pk_fma_f32 v[254:255], v[48:49], v[48:49], v[254:255]
	v_cvt_pk_bf16_f32 v54, v48, v49
	v_pk_fma_f32 v[254:255], v[50:51], v[50:51], v[254:255]
	v_cvt_pk_bf16_f32 v55, v50, v51
	global_store_dwordx4 v232, v[52:55], s[20:21] offset:256
	v_add_f32_e32 v48, v254, v255
	s_waitcnt vmcnt(15)
	v_lshlrev_b32_e32 v244, 16, v196
	v_and_b32_e32 v245, 0xffff0000, v196
	v_lshlrev_b32_e32 v246, 16, v197
	v_and_b32_e32 v247, 0xffff0000, v197
	v_lshlrev_b32_e32 v250, 16, v198
	v_and_b32_e32 v251, 0xffff0000, v198
	v_lshlrev_b32_e32 v252, 16, v199
	v_and_b32_e32 v253, 0xffff0000, v199
	v_pk_add_f32 v[44:45], v[44:45], v[244:245]
	v_pk_add_f32 v[46:47], v[46:47], v[246:247]
	v_pk_add_f32 v[40:41], v[40:41], v[250:251]
	v_pk_add_f32 v[42:43], v[42:43], v[252:253]
	v_pk_mul_f32 v[254:255], v[44:45], v[44:45]
	v_cvt_pk_bf16_f32 v44, v44, v45
	v_pk_fma_f32 v[254:255], v[46:47], v[46:47], v[254:255]
	v_cvt_pk_bf16_f32 v45, v46, v47
	v_pk_fma_f32 v[254:255], v[40:41], v[40:41], v[254:255]
	v_cvt_pk_bf16_f32 v46, v40, v41
	v_pk_fma_f32 v[254:255], v[42:43], v[42:43], v[254:255]
	v_cvt_pk_bf16_f32 v47, v42, v43
	global_store_dwordx4 v233, v[44:47], s[20:21]
	s_waitcnt vmcnt(15)
	v_lshlrev_b32_e32 v244, 16, v200
	v_and_b32_e32 v245, 0xffff0000, v200
	v_lshlrev_b32_e32 v246, 16, v201
	v_and_b32_e32 v247, 0xffff0000, v201
	v_lshlrev_b32_e32 v250, 16, v202
	v_and_b32_e32 v251, 0xffff0000, v202
	v_lshlrev_b32_e32 v252, 16, v203
	v_and_b32_e32 v253, 0xffff0000, v203
	v_pk_add_f32 v[36:37], v[36:37], v[244:245]
	v_pk_add_f32 v[38:39], v[38:39], v[246:247]
	v_pk_add_f32 v[32:33], v[32:33], v[250:251]
	v_pk_add_f32 v[34:35], v[34:35], v[252:253]
	v_pk_fma_f32 v[254:255], v[36:37], v[36:37], v[254:255]
	v_cvt_pk_bf16_f32 v36, v36, v37
	v_pk_fma_f32 v[254:255], v[38:39], v[38:39], v[254:255]
	v_cvt_pk_bf16_f32 v37, v38, v39
	v_pk_fma_f32 v[254:255], v[32:33], v[32:33], v[254:255]
	v_cvt_pk_bf16_f32 v38, v32, v33
	v_pk_fma_f32 v[254:255], v[34:35], v[34:35], v[254:255]
	v_cvt_pk_bf16_f32 v39, v34, v35
	global_store_dwordx4 v233, v[36:39], s[20:21] offset:256
	v_add_f32_e32 v32, v254, v255
	s_waitcnt vmcnt(15)
	v_lshlrev_b32_e32 v244, 16, v204
	v_and_b32_e32 v245, 0xffff0000, v204
	v_lshlrev_b32_e32 v246, 16, v205
	v_and_b32_e32 v247, 0xffff0000, v205
	v_lshlrev_b32_e32 v250, 16, v206
	v_and_b32_e32 v251, 0xffff0000, v206
	v_lshlrev_b32_e32 v252, 16, v207
	v_and_b32_e32 v253, 0xffff0000, v207
	v_pk_add_f32 v[28:29], v[28:29], v[244:245]
	v_pk_add_f32 v[30:31], v[30:31], v[246:247]
	v_pk_add_f32 v[24:25], v[24:25], v[250:251]
	v_pk_add_f32 v[26:27], v[26:27], v[252:253]
	v_pk_mul_f32 v[254:255], v[28:29], v[28:29]
	v_cvt_pk_bf16_f32 v28, v28, v29
	v_pk_fma_f32 v[254:255], v[30:31], v[30:31], v[254:255]
	v_cvt_pk_bf16_f32 v29, v30, v31
	v_pk_fma_f32 v[254:255], v[24:25], v[24:25], v[254:255]
	v_cvt_pk_bf16_f32 v30, v24, v25
	v_pk_fma_f32 v[254:255], v[26:27], v[26:27], v[254:255]
	v_cvt_pk_bf16_f32 v31, v26, v27
	global_store_dwordx4 v234, v[28:31], s[20:21]
	s_waitcnt vmcnt(15)
	v_lshlrev_b32_e32 v244, 16, v208
	v_and_b32_e32 v245, 0xffff0000, v208
	v_lshlrev_b32_e32 v246, 16, v209
	v_and_b32_e32 v247, 0xffff0000, v209
	v_lshlrev_b32_e32 v250, 16, v210
	v_and_b32_e32 v251, 0xffff0000, v210
	v_lshlrev_b32_e32 v252, 16, v211
	v_and_b32_e32 v253, 0xffff0000, v211
	v_pk_add_f32 v[20:21], v[20:21], v[244:245]
	v_pk_add_f32 v[22:23], v[22:23], v[246:247]
	v_pk_add_f32 v[16:17], v[16:17], v[250:251]
	v_pk_add_f32 v[18:19], v[18:19], v[252:253]
	v_pk_fma_f32 v[254:255], v[20:21], v[20:21], v[254:255]
	v_cvt_pk_bf16_f32 v20, v20, v21
	v_pk_fma_f32 v[254:255], v[22:23], v[22:23], v[254:255]
	v_cvt_pk_bf16_f32 v21, v22, v23
	v_pk_fma_f32 v[254:255], v[16:17], v[16:17], v[254:255]
	v_cvt_pk_bf16_f32 v22, v16, v17
	v_pk_fma_f32 v[254:255], v[18:19], v[18:19], v[254:255]
	v_cvt_pk_bf16_f32 v23, v18, v19
	global_store_dwordx4 v234, v[20:23], s[20:21] offset:256
	v_add_f32_e32 v16, v254, v255
	s_waitcnt vmcnt(15)
	v_lshlrev_b32_e32 v244, 16, v212
	v_and_b32_e32 v245, 0xffff0000, v212
	v_lshlrev_b32_e32 v246, 16, v213
	v_and_b32_e32 v247, 0xffff0000, v213
	v_lshlrev_b32_e32 v250, 16, v214
	v_and_b32_e32 v251, 0xffff0000, v214
	v_lshlrev_b32_e32 v252, 16, v215
	v_and_b32_e32 v253, 0xffff0000, v215
	v_pk_add_f32 v[12:13], v[12:13], v[244:245]
	v_pk_add_f32 v[14:15], v[14:15], v[246:247]
	v_pk_add_f32 v[8:9], v[8:9], v[250:251]
	v_pk_add_f32 v[10:11], v[10:11], v[252:253]
	v_pk_mul_f32 v[254:255], v[12:13], v[12:13]
	v_cvt_pk_bf16_f32 v12, v12, v13
	v_pk_fma_f32 v[254:255], v[14:15], v[14:15], v[254:255]
	v_cvt_pk_bf16_f32 v13, v14, v15
	v_pk_fma_f32 v[254:255], v[8:9], v[8:9], v[254:255]
	v_cvt_pk_bf16_f32 v14, v8, v9
	v_pk_fma_f32 v[254:255], v[10:11], v[10:11], v[254:255]
	v_cvt_pk_bf16_f32 v15, v10, v11
	global_store_dwordx4 v235, v[12:15], s[20:21]
	s_waitcnt vmcnt(15)
	v_lshlrev_b32_e32 v244, 16, v224
	v_and_b32_e32 v245, 0xffff0000, v224
	v_lshlrev_b32_e32 v246, 16, v225
	v_and_b32_e32 v247, 0xffff0000, v225
	v_lshlrev_b32_e32 v250, 16, v226
	v_and_b32_e32 v251, 0xffff0000, v226
	v_lshlrev_b32_e32 v252, 16, v227
	v_and_b32_e32 v253, 0xffff0000, v227
	v_pk_add_f32 v[4:5], v[4:5], v[244:245]
	v_pk_add_f32 v[6:7], v[6:7], v[246:247]
	v_pk_add_f32 v[0:1], v[0:1], v[250:251]
	v_pk_add_f32 v[2:3], v[2:3], v[252:253]
	v_pk_fma_f32 v[254:255], v[4:5], v[4:5], v[254:255]
	v_cvt_pk_bf16_f32 v4, v4, v5
	v_pk_fma_f32 v[254:255], v[6:7], v[6:7], v[254:255]
	v_cvt_pk_bf16_f32 v5, v6, v7
	v_pk_fma_f32 v[254:255], v[0:1], v[0:1], v[254:255]
	v_cvt_pk_bf16_f32 v6, v0, v1
	v_pk_fma_f32 v[254:255], v[2:3], v[2:3], v[254:255]
	v_cvt_pk_bf16_f32 v7, v2, v3
	global_store_dwordx4 v235, v[4:7], s[20:21] offset:256
	v_add_f32_e32 v0, v254, v255
	v_xor_b32_e32 v244, 16, v154
	v_xor_b32_e32 v245, 32, v154
	v_lshlrev_b32_e32 v244, 2, v244
	v_lshlrev_b32_e32 v245, 2, v245
	ds_bpermute_b32 v156, v244, v112
	ds_bpermute_b32 v157, v244, v96
	ds_bpermute_b32 v158, v244, v80
	ds_bpermute_b32 v159, v244, v64
	ds_bpermute_b32 v160, v244, v48
	ds_bpermute_b32 v161, v244, v32
	ds_bpermute_b32 v162, v244, v16
	ds_bpermute_b32 v163, v244, v0
	s_waitcnt lgkmcnt(0)
	v_add_f32_e32 v112, v112, v156
	v_add_f32_e32 v96, v96, v157
	v_add_f32_e32 v80, v80, v158
	v_add_f32_e32 v64, v64, v159
	v_add_f32_e32 v48, v48, v160
	v_add_f32_e32 v32, v32, v161
	v_add_f32_e32 v16, v16, v162
	v_add_f32_e32 v0, v0, v163
	ds_bpermute_b32 v156, v245, v112
	ds_bpermute_b32 v157, v245, v96
	ds_bpermute_b32 v158, v245, v80
	ds_bpermute_b32 v159, v245, v64
	ds_bpermute_b32 v160, v245, v48
	ds_bpermute_b32 v161, v245, v32
	ds_bpermute_b32 v162, v245, v16
	ds_bpermute_b32 v163, v245, v0
	v_lshlrev_b32_e32 v145, 2, v146
	s_waitcnt lgkmcnt(0)
	v_add_f32_e32 v112, v112, v156
	v_add_f32_e32 v96, v96, v157
	v_add_f32_e32 v80, v80, v158
	v_add_f32_e32 v64, v64, v159
	v_add_f32_e32 v48, v48, v160
	v_add_f32_e32 v32, v32, v161
	v_add_f32_e32 v16, v16, v162
	v_add_f32_e32 v0, v0, v163
	s_and_saveexec_b64 s[42:43], s[6:7]
	s_cbranch_execz .Lepi_p6_noatom
	global_atomic_add_f32 v145, v112, s[22:23]
	global_atomic_add_f32 v145, v96, s[22:23] offset:64
	global_atomic_add_f32 v145, v80, s[22:23] offset:128
	global_atomic_add_f32 v145, v64, s[22:23] offset:192
	global_atomic_add_f32 v145, v48, s[22:23] offset:512
	global_atomic_add_f32 v145, v32, s[22:23] offset:576
	global_atomic_add_f32 v145, v16, s[22:23] offset:640
	global_atomic_add_f32 v145, v0, s[22:23] offset:704
